# up GEMM rstd table: one wave per unit with dwordx4 plane loads (4 rows per lane, 176 load instrs per WG instead of 768), same per-row summation tree, pk_add
# speedup vs baseline: 1.0126x; 1.0033x over previous
.LBB0_381:
	v_readlane_b32 s4, v254, 8
	v_readlane_b32 s5, v254, 9
	s_andn2_b64 vcc, exec, s[4:5]
	v_readfirstlane_b32 s28, v248
	s_cbranch_vccnz .LBB0_412
	s_waitcnt vmcnt(0) lgkmcnt(0)
	s_lshr_b32 s4, s28, 6
	v_and_b32_e32 v2, 63, v248
	v_lshlrev_b32_e32 v2, 4, v2
	s_add_i32 s5, s4, 0
	s_lshl_b32 s6, s5, 8
	s_add_i32 s6, s6, s2
	s_and_b32 s7, s6, 7
	s_mul_i32 s7, s7, 0x160
	s_lshr_b32 s20, s6, 3
	s_add_i32 s7, s7, s20
	s_lshr_b32 s20, s7, 3
	s_mul_i32 s20, s20, 0x1746
	s_lshr_b32 s20, s20, 16
	s_mul_i32 s21, s20, 0x58
	s_sub_i32 s21, s7, s21
	s_and_b32 s21, s21, 3
	s_lshl_b32 s20, s20, 2
	s_add_i32 s20, s20, s21
	s_lshl_b32 s20, s20, 10
	v_add_u32_e32 v3, s20, v2
	global_load_dwordx4 v[4:7], v3, s[14:15]
	v_add_u32_e32 v3, 0x20000, v3
	global_load_dwordx4 v[8:11], v3, s[14:15]
	v_add_u32_e32 v3, 0x20000, v3
	global_load_dwordx4 v[12:15], v3, s[14:15]
	v_add_u32_e32 v3, 0x20000, v3
	global_load_dwordx4 v[16:19], v3, s[14:15]
	v_add_u32_e32 v3, 0x20000, v3
	global_load_dwordx4 v[20:23], v3, s[14:15]
	v_add_u32_e32 v3, 0x20000, v3
	global_load_dwordx4 v[24:27], v3, s[14:15]
	v_add_u32_e32 v3, 0x20000, v3
	global_load_dwordx4 v[28:31], v3, s[14:15]
	v_add_u32_e32 v3, 0x20000, v3
	global_load_dwordx4 v[32:35], v3, s[14:15]
	v_add_u32_e32 v3, 0x20000, v3
	global_load_dwordx4 v[36:39], v3, s[14:15]
	v_add_u32_e32 v3, 0x20000, v3
	global_load_dwordx4 v[40:43], v3, s[14:15]
	v_add_u32_e32 v3, 0x20000, v3
	global_load_dwordx4 v[44:47], v3, s[14:15]
	v_add_u32_e32 v3, 0x20000, v3
	global_load_dwordx4 v[48:51], v3, s[14:15]
	v_add_u32_e32 v3, 0x20000, v3
	global_load_dwordx4 v[52:55], v3, s[14:15]
	v_add_u32_e32 v3, 0x20000, v3
	global_load_dwordx4 v[56:59], v3, s[14:15]
	v_add_u32_e32 v3, 0x20000, v3
	global_load_dwordx4 v[60:63], v3, s[14:15]
	v_add_u32_e32 v3, 0x20000, v3
	global_load_dwordx4 v[64:67], v3, s[14:15]
	s_cmp_gt_u32 s4, 2
	s_cbranch_scc1 .Lupt_one
	s_add_i32 s5, s4, 8
	s_lshl_b32 s6, s5, 8
	s_add_i32 s6, s6, s2
	s_and_b32 s7, s6, 7
	s_mul_i32 s7, s7, 0x160
	s_lshr_b32 s20, s6, 3
	s_add_i32 s7, s7, s20
	s_lshr_b32 s20, s7, 3
	s_mul_i32 s20, s20, 0x1746
	s_lshr_b32 s20, s20, 16
	s_mul_i32 s21, s20, 0x58
	s_sub_i32 s21, s7, s21
	s_and_b32 s21, s21, 3
	s_lshl_b32 s20, s20, 2
	s_add_i32 s20, s20, s21
	s_lshl_b32 s20, s20, 10
	v_add_u32_e32 v3, s20, v2
	global_load_dwordx4 v[68:71], v3, s[14:15]
	v_add_u32_e32 v3, 0x20000, v3
	global_load_dwordx4 v[72:75], v3, s[14:15]
	v_add_u32_e32 v3, 0x20000, v3
	global_load_dwordx4 v[76:79], v3, s[14:15]
	v_add_u32_e32 v3, 0x20000, v3
	global_load_dwordx4 v[80:83], v3, s[14:15]
	v_add_u32_e32 v3, 0x20000, v3
	global_load_dwordx4 v[84:87], v3, s[14:15]
	v_add_u32_e32 v3, 0x20000, v3
	global_load_dwordx4 v[88:91], v3, s[14:15]
	v_add_u32_e32 v3, 0x20000, v3
	global_load_dwordx4 v[92:95], v3, s[14:15]
	v_add_u32_e32 v3, 0x20000, v3
	global_load_dwordx4 v[96:99], v3, s[14:15]
	v_add_u32_e32 v3, 0x20000, v3
	global_load_dwordx4 v[100:103], v3, s[14:15]
	v_add_u32_e32 v3, 0x20000, v3
	global_load_dwordx4 v[104:107], v3, s[14:15]
	v_add_u32_e32 v3, 0x20000, v3
	global_load_dwordx4 v[108:111], v3, s[14:15]
	v_add_u32_e32 v3, 0x20000, v3
	global_load_dwordx4 v[112:115], v3, s[14:15]
	v_add_u32_e32 v3, 0x20000, v3
	global_load_dwordx4 v[116:119], v3, s[14:15]
	v_add_u32_e32 v3, 0x20000, v3
	global_load_dwordx4 v[120:123], v3, s[14:15]
	v_add_u32_e32 v3, 0x20000, v3
	global_load_dwordx4 v[124:127], v3, s[14:15]
	v_add_u32_e32 v3, 0x20000, v3
	global_load_dwordx4 v[128:131], v3, s[14:15]
	s_waitcnt vmcnt(0)
	v_pk_add_f32 v[68:69], v[68:69], v[72:73]
	v_pk_add_f32 v[68:69], v[68:69], v[76:77]
	v_pk_add_f32 v[68:69], v[68:69], v[80:81]
	v_pk_add_f32 v[84:85], v[84:85], v[88:89]
	v_pk_add_f32 v[84:85], v[84:85], v[92:93]
	v_pk_add_f32 v[84:85], v[84:85], v[96:97]
	v_pk_add_f32 v[100:101], v[100:101], v[104:105]
	v_pk_add_f32 v[100:101], v[100:101], v[108:109]
	v_pk_add_f32 v[100:101], v[100:101], v[112:113]
	v_pk_add_f32 v[116:117], v[116:117], v[120:121]
	v_pk_add_f32 v[116:117], v[116:117], v[124:125]
	v_pk_add_f32 v[116:117], v[116:117], v[128:129]
	v_pk_add_f32 v[70:71], v[70:71], v[74:75]
	v_pk_add_f32 v[70:71], v[70:71], v[78:79]
	v_pk_add_f32 v[70:71], v[70:71], v[82:83]
	v_pk_add_f32 v[86:87], v[86:87], v[90:91]
	v_pk_add_f32 v[86:87], v[86:87], v[94:95]
	v_pk_add_f32 v[86:87], v[86:87], v[98:99]
	v_pk_add_f32 v[102:103], v[102:103], v[106:107]
	v_pk_add_f32 v[102:103], v[102:103], v[110:111]
	v_pk_add_f32 v[102:103], v[102:103], v[114:115]
	v_pk_add_f32 v[118:119], v[118:119], v[122:123]
	v_pk_add_f32 v[118:119], v[118:119], v[126:127]
	v_pk_add_f32 v[118:119], v[118:119], v[130:131]
	v_pk_add_f32 v[68:69], v[68:69], v[84:85]
	v_pk_add_f32 v[100:101], v[100:101], v[116:117]
	v_pk_add_f32 v[68:69], v[68:69], v[100:101]
	v_pk_add_f32 v[70:71], v[70:71], v[86:87]
	v_pk_add_f32 v[102:103], v[102:103], v[118:119]
	v_pk_add_f32 v[70:71], v[70:71], v[102:103]
	v_fma_f32 v68, v68, s90, v212
	v_fma_f32 v69, v69, s90, v212
	v_fma_f32 v70, v70, s90, v212
	v_fma_f32 v71, v71, s90, v212
	v_rsq_f32_e32 v68, v68
	v_rsq_f32_e32 v69, v69
	v_rsq_f32_e32 v70, v70
	v_rsq_f32_e32 v71, v71
	s_add_i32 s5, s4, 8
	s_lshl_b32 s5, s5, 10
	s_add_i32 s5, s5, 0x21000
	v_add_u32_e32 v3, s5, v2
	s_nop 0
	ds_write_b128 v3, v[68:71]
.Lupt_one:
	s_waitcnt vmcnt(0)
	v_pk_add_f32 v[4:5], v[4:5], v[8:9]
	v_pk_add_f32 v[4:5], v[4:5], v[12:13]
	v_pk_add_f32 v[4:5], v[4:5], v[16:17]
	v_pk_add_f32 v[20:21], v[20:21], v[24:25]
	v_pk_add_f32 v[20:21], v[20:21], v[28:29]
	v_pk_add_f32 v[20:21], v[20:21], v[32:33]
	v_pk_add_f32 v[36:37], v[36:37], v[40:41]
	v_pk_add_f32 v[36:37], v[36:37], v[44:45]
	v_pk_add_f32 v[36:37], v[36:37], v[48:49]
	v_pk_add_f32 v[52:53], v[52:53], v[56:57]
	v_pk_add_f32 v[52:53], v[52:53], v[60:61]
	v_pk_add_f32 v[52:53], v[52:53], v[64:65]
	v_pk_add_f32 v[6:7], v[6:7], v[10:11]
	v_pk_add_f32 v[6:7], v[6:7], v[14:15]
	v_pk_add_f32 v[6:7], v[6:7], v[18:19]
	v_pk_add_f32 v[22:23], v[22:23], v[26:27]
	v_pk_add_f32 v[22:23], v[22:23], v[30:31]
	v_pk_add_f32 v[22:23], v[22:23], v[34:35]
	v_pk_add_f32 v[38:39], v[38:39], v[42:43]
	v_pk_add_f32 v[38:39], v[38:39], v[46:47]
	v_pk_add_f32 v[38:39], v[38:39], v[50:51]
	v_pk_add_f32 v[54:55], v[54:55], v[58:59]
	v_pk_add_f32 v[54:55], v[54:55], v[62:63]
	v_pk_add_f32 v[54:55], v[54:55], v[66:67]
	v_pk_add_f32 v[4:5], v[4:5], v[20:21]
	v_pk_add_f32 v[36:37], v[36:37], v[52:53]
	v_pk_add_f32 v[4:5], v[4:5], v[36:37]
	v_pk_add_f32 v[6:7], v[6:7], v[22:23]
	v_pk_add_f32 v[38:39], v[38:39], v[54:55]
	v_pk_add_f32 v[6:7], v[6:7], v[38:39]
	v_fma_f32 v4, v4, s90, v212
	v_fma_f32 v5, v5, s90, v212
	v_fma_f32 v6, v6, s90, v212
	v_fma_f32 v7, v7, s90, v212
	v_rsq_f32_e32 v4, v4
	v_rsq_f32_e32 v5, v5
	v_rsq_f32_e32 v6, v6
	v_rsq_f32_e32 v7, v7
	s_add_i32 s5, s4, 0
	s_lshl_b32 s5, s5, 10
	s_add_i32 s5, s5, 0x21000
	v_add_u32_e32 v3, s5, v2
	s_nop 0
	ds_write_b128 v3, v[4:7]
	s_waitcnt lgkmcnt(0)
	v_lshlrev_b32_e32 v0, 4, v248
	s_waitcnt vmcnt(0)
	v_add_u32_e32 v2, 0x2000, v0
	s_waitcnt vmcnt(4)
	v_ashrrev_i32_e32 v3, 31, v2
	v_lshrrev_b32_e32 v3, 22, v3
	v_add_u32_e32 v3, v2, v3
	v_ashrrev_i32_e32 v10, 10, v3
	v_mul_i32_i24_e32 v3, 0x400, v10
	v_sub_u32_e32 v2, v2, v3
	v_lshrrev_b32_e32 v3, 4, v2
	v_bitop3_b32 v2, v3, v2, 32 bitop3:0x6c
	v_ashrrev_i32_e32 v3, 31, v2
	s_mul_i32 s5, s16, 0xb00000
	v_lshrrev_b32_e32 v3, 26, v3
	s_mul_hi_i32 s4, s16, 0xb00000
	s_add_u32 s5, s8, s5
	v_add_u32_e32 v3, v2, v3
	v_lshlrev_b32_e32 v5, 3, v10
	s_addc_u32 s4, s9, s4
	v_ashrrev_i32_e32 v4, 6, v3
	v_and_b32_e32 v5, -16, v5
	v_and_b32_e32 v3, 0xc0, v3
	s_add_u32 s17, s5, 0x1000000
	v_add_u32_e32 v5, v4, v5
	v_sub_u32_e32 v2, v2, v3
	s_addc_u32 s70, s4, 0
	v_lshlrev_b32_e32 v6, 1, v5
	v_lshlrev_b32_e32 v7, 3, v5
	v_lshlrev_b32_e32 v8, 5, v10
	v_ashrrev_i16_sdwa v2, v214, sext(v2) dst_sel:DWORD dst_unused:UNUSED_PAD src0_sel:DWORD src1_sel:BYTE_0
	v_and_b32_e32 v3, 3, v4
	s_mov_b32 s4, 0x1fffe0
	v_lshrrev_b32_e32 v4, 2, v5
	v_and_b32_e32 v11, 0x1fff80, v6
	v_and_b32_e32 v12, 0x78, v7
	v_bfe_u32 v13, v5, 4, 2
	v_and_b32_e32 v8, 32, v8
	v_bfe_i32 v14, v2, 0, 16
	v_and_or_b32 v3, v5, s4, v3
	v_and_b32_e32 v4, 4, v4
	v_and_b32_e32 v5, 24, v6
	v_or3_b32 v7, v11, v12, v13
	v_add_lshl_u32 v2, v8, v14, 1
	v_or3_b32 v3, v3, v4, v5
	v_lshl_add_u32 v222, v7, 11, v2
	v_lshl_add_u32 v224, v3, 11, v2
	v_bfe_i32 v2, v248, 27, 1
	v_lshrrev_b32_e32 v2, 22, v2
	v_add_u32_e32 v2, v0, v2
	v_and_b32_e32 v2, 0xfffffc00, v2
	v_sub_u32_e32 v0, v0, v2
	v_lshrrev_b32_e32 v2, 4, v0
	v_ashrrev_i32_e32 v4, 31, v248
	v_bitop3_b32 v0, v2, v0, 32 bitop3:0x6c
	v_lshrrev_b32_e32 v4, 26, v4
	v_ashrrev_i32_e32 v2, 31, v0
	v_add_u32_e32 v4, v248, v4
	v_lshrrev_b32_e32 v2, 26, v2
	v_ashrrev_i32_e32 v15, 6, v4
	v_add_u32_e32 v2, v0, v2
	v_lshlrev_b32_e32 v4, 3, v15
	v_ashrrev_i32_e32 v3, 6, v2
	v_and_b32_e32 v4, -16, v4
	v_and_b32_e32 v2, 0xc0, v2
	s_ashr_i32 s29, s28, 6
	v_add_u32_e32 v4, v3, v4
	v_sub_u32_e32 v0, v0, v2
	v_and_b32_e32 v2, 3, v3
	s_ashr_i32 s71, s28, 8
	s_lshl_b32 s74, s29, 10
	v_lshlrev_b32_e32 v5, 1, v4
	v_lshlrev_b32_e32 v6, 3, v4
	v_lshlrev_b32_e32 v7, 5, v15
	v_ashrrev_i16_sdwa v0, v214, sext(v0) dst_sel:DWORD dst_unused:UNUSED_PAD src0_sel:DWORD src1_sel:BYTE_0
	v_and_or_b32 v2, v4, s4, v2
	v_lshrrev_b32_e32 v3, 2, v4
	v_readlane_b32 s4, v254, 54
	v_and_b32_e32 v16, 0x1fff80, v5
	v_and_b32_e32 v17, 0x78, v6
	s_waitcnt vmcnt(3)
	v_bfe_u32 v18, v4, 4, 2
	v_and_b32_e32 v7, 32, v7
	v_bfe_i32 v19, v0, 0, 16
	v_and_b32_e32 v3, 4, v3
	v_and_b32_e32 v4, 24, v5
	v_readlane_b32 s5, v254, 55
	s_add_u32 s38, s17, s4
	v_or3_b32 v6, v16, v17, v18
	v_add_lshl_u32 v0, v7, v19, 1
	v_or3_b32 v2, v2, v3, v4
	s_addc_u32 s39, s70, s5
	s_add_i32 s75, s74, 0
	v_lshl_add_u32 v226, v6, 11, v0
	v_lshl_add_u32 v0, v2, 11, v0
	s_add_i32 m0, s75, 0x10000
	v_writelane_b32 v255, s30, 15
	global_load_lds_dwordx4 v0, s[38:39]
	s_add_i32 m0, s75, 0x12000
	s_add_u32 s4, s38, 0x40000
	global_load_lds_dwordx4 v224, s[38:39]
	s_addc_u32 s5, s39, 0
	s_add_i32 m0, s75, 0x14000
	v_mov_b32_e32 v225, v1
	global_load_lds_dwordx4 v0, s[4:5]
	s_add_i32 m0, s75, 0x16000
	v_mov_b32_e32 v227, v1
	global_load_lds_dwordx4 v224, s[4:5]
	v_readlane_b32 s4, v255, 4
	v_readlane_b32 s5, v255, 5
	s_add_u32 s42, s12, s4
	s_addc_u32 s43, s13, s5
	s_add_i32 s76, s75, 0x2000
	s_mov_b32 m0, s75
	s_add_u32 s4, s42, 0x2000
	global_load_lds_dwordx4 v226, s[42:43]
	s_mov_b32 m0, s76
	s_addc_u32 s5, s43, 0
	s_add_i32 s77, s75, 0x4000
	global_load_lds_dwordx4 v222, s[42:43]
	s_mov_b32 m0, s77
	s_add_i32 s78, s75, 0x6000
	global_load_lds_dwordx4 v226, s[4:5]
	s_mov_b32 m0, s78
	s_cmp_eq_u32 s71, 1
	global_load_lds_dwordx4 v222, s[4:5]
	s_load_dwordx2 s[26:27], s[0:1], 0x48
	s_load_dword s79, s[88:89], 0x0
	s_cselect_b64 s[24:25], -1, 0
	s_cmp_lg_u32 s71, 1
	v_mov_b32_e32 v223, v1
	s_cselect_b64 s[44:45], -1, 0
	v_lshl_add_u64 v[8:9], s[38:39], 0, v[0:1]
	v_lshl_add_u64 v[6:7], s[38:39], 0, v[224:225]
	v_lshl_add_u64 v[4:5], s[42:43], 0, v[226:227]
	v_lshl_add_u64 v[2:3], s[42:43], 0, v[222:223]
	s_and_b64 vcc, exec, s[44:45]
	s_cbranch_vccnz .LBB0_384
	s_barrier
